# owner runs 4 instead of 5 unclaimed phaseA passes
# speedup vs baseline: 1.0345x; 1.0001x over previous
;     ...
; #pragma unroll 1
;     for (int pass = 0; pass * NWAVE < NU; ++pass) {
;         const int unit = pass * NWAVE + wave;
;         const bool active = unit < NU;
;         const int ucl = active ? unit : NU - 1;
;         const u32x4* bp = Bw + (size_t)(ucl * NT) * 64 + lane;
;         const size_t kstr = (size_t)NU * NT * 64;
.LBB0_822:
	s_or_b64 exec, exec, s[8:9]
	s_add_i32 s88, s88, 1
	s_cmp_lt_u32 s88, 4
	s_cbranch_scc1 .Lm3a_go
	v_readlane_b32 s10, v252, 10
	v_readlane_b32 s11, v252, 11
	s_lshl_b32 s6, s90, 2
	s_add_u32 s6, s6, s31
	s_lshl_b32 s6, s6, 3
	s_add_u32 s10, s10, s6
	s_addc_u32 s11, s11, 0

;     ...
; #pragma unroll 1
;     for (int pass = 0; pass * NWAVE < NU; ++pass) {
;         const int unit = pass * NWAVE + wave;
;         const bool active = unit < NU;
;         const int ucl = active ? unit : NU - 1;
.Lm3a_c_w:
	s_barrier
	ds_read_b32 v3, v2
	s_waitcnt lgkmcnt(0)
	v_readfirstlane_b32 s88, v3
	s_nop 3
	s_add_u32 s88, s88, 4
	s_cmp_ge_u32 s88, 9
	s_cbranch_scc1 .LBB0_781

;     ...
; #pragma unroll 1
;     for (int pass = 0; pass * NWAVE < NU; ++pass) {
;         const int unit = pass * NWAVE + wave;
;         const bool active = unit < NU;
;         const int ucl = active ? unit : NU - 1;
.Lha_c_w:
	s_barrier
	ds_read_b32 v3, v2
	s_waitcnt lgkmcnt(0)
	v_readfirstlane_b32 s88, v3
	s_nop 3
	s_add_u32 s88, s88, 4
	s_cmp_ge_u32 s88, 9
	s_cbranch_scc1 .Lha_next
	s_lshl_b32 s2, s88, 3
	v_add_u32_e32 v232, s2, v223
